# PRE2 Kc table loop moved onto the 128 workgroups that have no tile in the following memory K/V projection GEMM
# baseline (speedup 1.0000x reference)
; #define FRESH_IDS() int tid_ = threadIdx.x; asm volatile("" : "+v"(tid_)); const int lane = tid_ & 63; const int gt = bx * (NWAVES * 64) + tid_; (void)lane; (void)gt
; #define INP(j) (((PH_EN >> (12 + (j))) & 1u) && IN(j))
; __global__ void __launch_bounds__(NWAVES * 64, 2) hybrid_fwd(Args args) {
;     ...
;     if (INP(1)) { FRESH_IDS();
;         for (int idx = gt; idx < DEPTH * NG * TCH * 256; idx += NGT) {
;             const int cp = idx & 15, c = (idx >> 4) & 15, tau = (idx >> 8) & 31, lg = idx >> 13;
;             const float* cre = args.in[10] + (size_t)(lg * 16 + c) * 64; const float* cim = args.in[11] + (size_t)(lg * 16 + c) * 64;
;             const float* bre = args.in[8] + (size_t)lg * 64 * 16 + cp; const float* bim = args.in[9] + (size_t)lg * 64 * 16 + cp;
;             const f32x2* lp = LP + (size_t)(lg * 33 + tau) * 64; const f32x2* cf = CF + (size_t)lg * 64;
;             float s = 0.f;
.LBB0_94:
	s_cmp_lt_i32 s66, 2
	s_cselect_b64 s[2:3], -1, 0
	s_add_u32 s6, s58, 0x9c00000
	s_addc_u32 s7, s59, 0
	v_writelane_b32 v249, s6, 45
	s_nop 1
	v_writelane_b32 v249, s7, 46
	s_add_u32 s6, s58, 0x47700000
	s_addc_u32 s7, s59, 0
	v_writelane_b32 v249, s6, 47
	s_and_b64 s[2:3], s[2:3], s[4:5]
	s_andn2_b64 vcc, exec, s[2:3]
	v_writelane_b32 v249, s7, 48
	v_writelane_b32 v249, s56, 49
	s_nop 1
	v_writelane_b32 v249, s57, 50
	v_writelane_b32 v249, s58, 51
	v_writelane_b32 v249, s59, 52
	s_cbranch_vccnz .LBB0_124
	v_mov_b32_e32 v1, v0
	v_readlane_b32 s4, v249, 0
	s_nop 1
	s_sub_i32 s100, s4, 0x80
	s_cmp_lt_i32 s100, 0
	s_cselect_b32 s100, 0x800, s100
	v_lshl_add_u32 v2, s100, 9, v1
	s_mov_b32 s4, 0x100000
	v_cmp_gt_i32_e32 vcc, s4, v2
	s_and_saveexec_b64 s[4:5], vcc
	s_cbranch_execz .LBB0_100
	v_and_b32_e32 v1, 15, v1
	v_mov_b32_e32 v7, 0
	v_lshlrev_b32_e32 v4, 2, v1
	v_mov_b32_e32 v5, v7
	s_mov_b64 s[6:7], 0
	s_mov_b64 s[8:9], 0xa000000
	s_mov_b64 s[10:11], 0xa240000
	s_mov_b64 s[14:15], 0x100
	s_mov_b32 s22, 0xfffff

; __global__ void __launch_bounds__(NWAVES * 64, 2) hybrid_fwd(Args args) {
;     ...
;         for (int idx = gt; idx < DEPTH * NG * TCH * 256; idx += NGT) {
;             const int cp = idx & 15, c = (idx >> 4) & 15, tau = (idx >> 8) & 31, lg = idx >> 13;
;             const float* cre = args.in[10] + (size_t)(lg * 16 + c) * 64; const float* cim = args.in[11] + (size_t)(lg * 16 + c) * 64;
;             const float* bre = args.in[8] + (size_t)lg * 64 * 16 + cp; const float* bim = args.in[9] + (size_t)lg * 64 * 16 + cp;
;             const f32x2* lp = LP + (size_t)(lg * 33 + tau) * 64; const f32x2* cf = CF + (size_t)lg * 64;
;             float s = 0.f;
;             for (int p = 0; p < 64; ++p) {
;                 const f32x2 w = lp[p], f = cf[p]; const float wr_ = w.x * f.x - w.y * f.y, wi_ = w.x * f.y + w.y * f.x;
;                 const float br = bre[p * 16], bi = bim[p * 16]; const float xr = wr_ * br - wi_ * bi, xi = wr_ * bi + wi_ * br;
;                 s += cre[p] * xr - cim[p] * xi;
;             }
;             KC[idx] = s;
;         }
.LBB0_98:
	v_lshl_add_u64 v[26:27], v[14:15], 0, s[18:19]
	v_lshl_add_u64 v[30:31], v[26:27], 0, s[8:9]
	v_add_co_u32_e32 v26, vcc, 0xa000000, v26
	v_lshl_add_u64 v[34:35], v[16:17], 0, s[18:19]
	s_nop 0
	v_addc_co_u32_e32 v27, vcc, 0, v27, vcc
	v_lshl_add_u64 v[28:29], v[12:13], 0, v[4:5]
	v_lshl_add_u64 v[18:19], s[16:17], 0, v[8:9]
	v_lshl_add_u64 v[22:23], s[20:21], 0, v[8:9]
	v_lshl_add_u64 v[38:39], v[34:35], 0, s[10:11]
	v_add_co_u32_e32 v34, vcc, 0xa240000, v34
	v_lshl_add_u64 v[42:43], v[10:11], 0, v[4:5]
	global_load_dwordx4 v[18:21], v[18:19], off
	s_nop 0
	global_load_dwordx4 v[22:25], v[22:23], off
	s_nop 0
	global_load_dword v6, v[42:43], off
	global_load_dword v44, v[42:43], off offset:64
	global_load_dword v46, v[42:43], off offset:128
	global_load_dword v48, v[28:29], off
	global_load_dword v50, v[28:29], off offset:64
	global_load_dword v52, v[28:29], off offset:128
	global_load_dword v54, v[28:29], off offset:192
	s_nop 0
	global_load_dwordx4 v[26:29], v[26:27], off
	s_nop 0
	global_load_dwordx4 v[30:33], v[30:31], off offset:16
	v_addc_co_u32_e32 v35, vcc, 0, v35, vcc
	global_load_dwordx4 v[34:37], v[34:35], off
	s_nop 0
	global_load_dwordx4 v[38:41], v[38:39], off offset:16
	s_nop 0
	global_load_dword v42, v[42:43], off offset:192
	s_add_u32 s20, s20, 16
	s_addc_u32 s21, s21, 0
	s_add_u32 s18, s18, 32
	s_addc_u32 s19, s19, 0
	s_add_u32 s16, s16, 16
	s_addc_u32 s17, s17, 0
	v_lshl_add_u64 v[10:11], v[10:11], 0, s[14:15]
	v_lshl_add_u64 v[12:13], v[12:13], 0, s[14:15]
	s_cmpk_eq_i32 s18, 0x200
	s_waitcnt vmcnt(13)
	v_mov_b32_e32 v56, v18
	v_mov_b32_e32 v18, v20
	s_waitcnt vmcnt(12)
	v_mov_b32_e32 v57, v22
	v_mov_b32_e32 v22, v19
	v_mov_b32_e32 v19, v24
	v_mov_b32_e32 v24, v21
	s_waitcnt vmcnt(4)
	v_mov_b32_e32 v20, v29
	s_waitcnt vmcnt(3)
	v_mov_b32_e32 v58, v33
	s_waitcnt vmcnt(2)
	v_pk_mul_f32 v[60:61], v[26:27], v[34:35] op_sel:[1,1] op_sel_hi:[1,0]
	v_pk_mul_f32 v[20:21], v[20:21], v[36:37] op_sel:[0,1] op_sel_hi:[0,0]
	s_waitcnt vmcnt(1)
	v_pk_mul_f32 v[62:63], v[30:31], v[38:39] op_sel:[1,1] op_sel_hi:[1,0]
	v_pk_fma_f32 v[64:65], v[26:27], v[34:35], v[60:61] op_sel_hi:[0,1,1] neg_lo:[0,0,1] neg_hi:[0,0,1]
	v_pk_fma_f32 v[26:27], v[26:27], v[34:35], v[60:61] op_sel_hi:[0,1,1]
	v_pk_mul_f32 v[58:59], v[58:59], v[40:41] op_sel:[0,1] op_sel_hi:[0,0]
	v_pk_fma_f32 v[34:35], v[28:29], v[36:37], v[20:21] op_sel_hi:[0,1,1] neg_lo:[0,0,1] neg_hi:[0,0,1]
	v_pk_fma_f32 v[20:21], v[28:29], v[36:37], v[20:21] op_sel_hi:[0,1,1]
	v_pk_fma_f32 v[28:29], v[30:31], v[38:39], v[62:63] op_sel_hi:[0,1,1] neg_lo:[0,0,1] neg_hi:[0,0,1]
	v_pk_fma_f32 v[30:31], v[30:31], v[38:39], v[62:63] op_sel_hi:[0,1,1]
	v_mov_b32_e32 v39, v27
	v_pk_mov_b32 v[26:27], v[26:27], v[64:65] op_sel:[1,0]
	v_pk_fma_f32 v[36:37], v[32:33], v[40:41], v[58:59] op_sel_hi:[0,1,1] neg_lo:[0,0,1] neg_hi:[0,0,1]
	v_pk_fma_f32 v[32:33], v[32:33], v[40:41], v[58:59] op_sel_hi:[0,1,1]
	v_mov_b32_e32 v38, v64
	v_mov_b32_e32 v41, v21
	v_pk_mov_b32 v[20:21], v[20:21], v[34:35] op_sel:[1,0]
	v_pk_mul_f32 v[26:27], v[48:49], v[26:27] op_sel_hi:[0,1]
	v_mov_b32_e32 v40, v34
	v_mov_b32_e32 v59, v31
	v_pk_mov_b32 v[30:31], v[30:31], v[28:29] op_sel:[1,0]
	v_pk_mul_f32 v[20:21], v[50:51], v[20:21] op_sel_hi:[0,1]
	v_pk_fma_f32 v[48:49], v[6:7], v[64:65], v[26:27] neg_lo:[0,0,1] neg_hi:[0,0,1]
	v_pk_fma_f32 v[26:27], v[6:7], v[38:39], v[26:27] op_sel_hi:[0,1,1]
	v_mov_b32_e32 v58, v28
	v_mov_b32_e32 v61, v33
	v_pk_mov_b32 v[32:33], v[32:33], v[36:37] op_sel:[1,0]
	v_pk_mul_f32 v[30:31], v[52:53], v[30:31] op_sel_hi:[0,1]
	v_pk_fma_f32 v[34:35], v[44:45], v[34:35], v[20:21] neg_lo:[0,0,1] neg_hi:[0,0,1]
	v_pk_fma_f32 v[20:21], v[44:45], v[40:41], v[20:21] op_sel_hi:[0,1,1]
	v_mov_b32_e32 v49, v27
	v_mov_b32_e32 v60, v36
	v_pk_mul_f32 v[32:33], v[54:55], v[32:33] op_sel_hi:[0,1]
	v_pk_fma_f32 v[28:29], v[46:47], v[28:29], v[30:31] neg_lo:[0,0,1] neg_hi:[0,0,1]
	v_pk_fma_f32 v[30:31], v[46:47], v[58:59], v[30:31] op_sel_hi:[0,1,1]
	v_mov_b32_e32 v35, v21
	v_pk_mul_f32 v[20:21], v[56:57], v[48:49]
	s_waitcnt vmcnt(0)
	v_pk_fma_f32 v[36:37], v[42:43], v[36:37], v[32:33] neg_lo:[0,0,1] neg_hi:[0,0,1]
	v_pk_fma_f32 v[32:33], v[42:43], v[60:61], v[32:33] op_sel_hi:[0,1,1]
	v_mov_b32_e32 v29, v31
	v_pk_mul_f32 v[22:23], v[22:23], v[34:35]
	v_sub_f32_e32 v3, v20, v21
	v_mov_b32_e32 v37, v33
	v_pk_mul_f32 v[18:19], v[18:19], v[28:29]
	v_sub_f32_e32 v6, v22, v23
	v_add_f32_e32 v1, v1, v3
	v_pk_mul_f32 v[24:25], v[24:25], v[36:37]
	v_sub_f32_e32 v18, v18, v19
	v_add_f32_e32 v1, v1, v6
	v_sub_f32_e32 v19, v24, v25
	v_add_f32_e32 v1, v1, v18
	v_add_f32_e32 v1, v1, v19
	s_cbranch_scc0 .LBB0_98
	v_readlane_b32 s16, v249, 45
	v_ashrrev_i32_e32 v3, 31, v2
	v_readlane_b32 s17, v249, 46
	s_mov_b32 s68, s24
	s_nop 0
	v_lshl_add_u64 v[8:9], v[2:3], 2, s[16:17]
	s_lshr_b32 s100, s68, 1
	v_add_u32_e32 v2, s100, v2
	v_cmp_lt_i32_e32 vcc, s22, v2
	s_or_b64 s[6:7], vcc, s[6:7]
	global_store_dword v[8:9], v1, off
	s_andn2_b64 exec, exec, s[6:7]
	s_cbranch_execnz .LBB0_97
